# P1: small-GEMM units of the sample rows all given to the 64 workgroups that have one 256x256 unit fewer
# baseline (speedup 1.0000x reference)
.LBB0_426:
	v_mov_b32_e32 v2, v0
	s_cmp_lt_u32 s36, 64
	s_cselect_b32 s36, s36, 0x240
	s_cmpk_gt_i32 s36, 0x23f
	v_readfirstlane_b32 s0, v2
	s_cbranch_scc1 .LBB0_431
	s_ashr_i32 s6, s0, 6
	s_mul_hi_i32 s0, s36, 0x38e38e39
	s_lshr_b32 s1, s0, 31
	s_ashr_i32 s0, s0, 3
	s_add_i32 s0, s0, s1
	s_mul_i32 s1, s0, 36
	s_lshl_b32 s0, s0, 6
	v_and_b32_e32 v198, 31, v2
	s_add_i32 s0, s0, 0x8000
	v_or_b32_e32 v4, s0, v198
	s_sub_i32 s2, s36, s1
	v_ashrrev_i32_e32 v5, 31, v4
	s_lshl_b32 s0, s6, 7
	v_lshlrev_b64 v[4:5], 11, v[4:5]
	s_ashr_i32 s1, s0, 31
	v_lshl_or_b32 v8, s2, 6, v198
	v_lshl_add_u64 v[4:5], s[70:71], 0, v[4:5]
	s_lshl_b64 s[0:1], s[0:1], 1
	v_lshrrev_b32_e32 v3, 1, v2
	v_ashrrev_i32_e32 v9, 31, v8
	v_readlane_b32 s8, v253, 24
	v_lshl_add_u64 v[4:5], v[4:5], 0, s[0:1]
	v_and_b32_e32 v6, 16, v3
	v_mov_b32_e32 v7, 0
	v_lshlrev_b64 v[8:9], 11, v[8:9]
	v_readlane_b32 s12, v253, 28
	v_readlane_b32 s13, v253, 29
	v_lshl_add_u64 v[4:5], v[4:5], 0, v[6:7]
	s_mov_b32 s2, 0x10000
	v_lshl_add_u64 v[8:9], s[12:13], 0, v[8:9]
	v_lshl_add_u64 v[8:9], v[8:9], 0, s[0:1]
	v_add_co_u32_e32 v10, vcc, s2, v4
	v_lshl_add_u64 v[8:9], v[8:9], 0, v[6:7]
	s_nop 0
	v_addc_co_u32_e32 v11, vcc, 0, v5, vcc
	v_add_co_u32_e32 v12, vcc, s2, v8
	s_add_u32 s4, s70, s0
	s_nop 0
	v_addc_co_u32_e32 v13, vcc, 0, v9, vcc
	global_load_dwordx4 v[102:105], v[4:5], off
	global_load_dwordx4 v[114:117], v[4:5], off offset:32
	global_load_dwordx4 v[98:101], v[8:9], off
	global_load_dwordx4 v[94:97], v[8:9], off offset:32
	global_load_dwordx4 v[126:129], v[10:11], off
	global_load_dwordx4 v[122:125], v[10:11], off offset:32
	global_load_dwordx4 v[118:121], v[12:13], off
	global_load_dwordx4 v[110:113], v[12:13], off offset:32
	global_load_dwordx4 v[106:109], v[4:5], off offset:64
	global_load_dwordx4 v[78:81], v[4:5], off offset:96
	global_load_dwordx4 v[82:85], v[8:9], off offset:64
	global_load_dwordx4 v[66:69], v[8:9], off offset:96
	global_load_dwordx4 v[90:93], v[10:11], off offset:64
	global_load_dwordx4 v[74:77], v[10:11], off offset:96
	global_load_dwordx4 v[86:89], v[12:13], off offset:64
	global_load_dwordx4 v[70:73], v[12:13], off offset:96
	s_addc_u32 s5, s71, s1
	s_add_u32 s0, s12, s0
	s_addc_u32 s1, s13, s1
	v_lshlrev_b32_e32 v4, 2, v2
	v_lshl_add_u64 v[196:197], s[0:1], 0, v[6:7]
	s_lshl_b32 s0, s6, 14
	v_and_b32_e32 v200, 60, v4
	v_ashrrev_i32_e32 v201, 4, v2
	v_add_u32_e32 v2, 0x200, v2
	s_add_i32 s0, s0, 0
	v_lshl_add_u32 v4, v200, 2, 0
	v_ashrrev_i32_e32 v207, 4, v2
	v_lshl_add_u64 v[194:195], s[4:5], 0, v[6:7]
	v_lshl_add_u32 v3, v198, 8, s0
	v_lshl_add_u32 v202, v201, 8, v4
	v_lshl_add_u32 v208, v207, 8, v4
	s_movk_i32 s5, 0x1000
	v_or_b32_e32 v199, 0x8000, v198
	v_add_u32_e32 v203, 0x10000, v202
	v_add_u32_e32 v204, 0x14000, v202
	v_add_u32_e32 v205, 0x18000, v202
	v_add_u32_e32 v206, 0x1c000, v202
	v_add_u32_e32 v209, 0x10000, v208
	v_add_u32_e32 v210, 0x14000, v208
	v_add_u32_e32 v211, 0x18000, v208
	v_add_u32_e32 v212, 0x1c000, v208
	s_lshl_b32 s4, s36, 6
	v_or_b32_e32 v213, s5, v198
	v_add_u32_e32 v214, v3, v6
	s_movk_i32 s6, 0x1200
	v_readlane_b32 s9, v253, 25
	v_readlane_b32 s10, v253, 26
	v_readlane_b32 s11, v253, 27
	v_readlane_b32 s14, v253, 30
	v_readlane_b32 s15, v253, 31
	v_readlane_b32 s16, v253, 32
	v_readlane_b32 s17, v253, 33
	v_readlane_b32 s18, v253, 34
	v_readlane_b32 s19, v253, 35
	v_readlane_b32 s20, v253, 36
	v_readlane_b32 s21, v253, 37
	v_readlane_b32 s22, v253, 38
	v_readlane_b32 s23, v253, 39
	s_branch .LBB0_429

.LBB0_429:
	s_waitcnt vmcnt(0)
	v_mfma_f32_32x32x16_bf16 v[50:65], v[98:101], v[102:105], 0
	s_mul_hi_i32 s0, s36, 0x38e38e39
	s_lshr_b32 s1, s0, 31
	s_ashr_i32 s0, s0, 3
	s_add_i32 s8, s0, s1
	s_add_i32 s36, s36, 64
	s_cmpk_gt_i32 s36, 0x23f
	s_cselect_b64 s[0:1], -1, 0
	v_mfma_f32_32x32x16_bf16 v[18:33], v[98:101], v[126:129], 0
	s_lshl_b32 s7, s8, 6
	s_mulk_i32 s8, 0xf700
	s_add_i32 s8, s8, s4
	v_mfma_f32_32x32x16_bf16 v[50:65], v[94:97], v[114:117], v[50:65]
	v_mfma_f32_32x32x16_bf16 v[18:33], v[94:97], v[122:125], v[18:33]
	v_add_u32_e32 v94, s7, v199
	v_ashrrev_i32_e32 v95, 31, v94
	v_lshlrev_b64 v[94:95], 11, v[94:95]
	v_add_u32_e32 v96, s8, v198
	v_lshl_add_u64 v[94:95], v[194:195], 0, v[94:95]
	v_ashrrev_i32_e32 v97, 31, v96
	v_lshlrev_b64 v[96:97], 11, v[96:97]
	v_mfma_f32_32x32x16_bf16 v[50:65], v[82:85], v[106:109], v[50:65]
	v_lshl_add_u64 v[96:97], v[196:197], 0, v[96:97]
	v_mfma_f32_32x32x16_bf16 v[18:33], v[82:85], v[90:93], v[18:33]
	v_add_co_u32_e32 v82, vcc, s2, v94
	s_nop 1
	v_addc_co_u32_e32 v83, vcc, 0, v95, vcc
	v_add_co_u32_e32 v84, vcc, s2, v96
	v_mfma_f32_32x32x16_bf16 v[34:49], v[118:121], v[102:105], 0
	s_nop 0
	v_addc_co_u32_e32 v85, vcc, 0, v97, vcc
	global_load_dwordx4 v[166:169], v[96:97], off offset:128
	global_load_dwordx4 v[150:153], v[96:97], off offset:160
	global_load_dwordx4 v[170:173], v[84:85], off offset:128
	global_load_dwordx4 v[154:157], v[84:85], off offset:160
	global_load_dwordx4 v[142:145], v[96:97], off offset:192
	global_load_dwordx4 v[138:141], v[96:97], off offset:224
	global_load_dwordx4 v[146:149], v[84:85], off offset:192
	global_load_dwordx4 v[130:133], v[84:85], off offset:224
	global_load_dwordx4 v[190:193], v[94:95], off offset:128
	global_load_dwordx4 v[182:185], v[94:95], off offset:160
	global_load_dwordx4 v[186:189], v[82:83], off offset:128
	global_load_dwordx4 v[178:181], v[82:83], off offset:160
	global_load_dwordx4 v[162:165], v[82:83], off offset:192
	global_load_dwordx4 v[174:177], v[94:95], off offset:192
	global_load_dwordx4 v[158:161], v[94:95], off offset:224
	global_load_dwordx4 v[134:137], v[82:83], off offset:224
	s_and_b64 vcc, exec, s[0:1]
	s_waitcnt vmcnt(15)
	v_mov_b64_e32 v[98:99], v[166:167]
	v_mfma_f32_32x32x16_bf16 v[2:17], v[118:121], v[126:129], 0
	s_waitcnt vmcnt(13)
	v_mov_b64_e32 v[118:119], v[170:171]
	v_mov_b64_e32 v[94:95], v[150:151]
	s_waitcnt vmcnt(11)
	v_mov_b64_e32 v[82:83], v[142:143]
	s_waitcnt vmcnt(7)
	v_mov_b64_e32 v[102:103], v[190:191]
	s_waitcnt vmcnt(5)
	v_mov_b64_e32 v[126:127], v[186:187]
	v_mov_b64_e32 v[100:101], v[168:169]
	v_mov_b64_e32 v[120:121], v[172:173]
	v_mfma_f32_32x32x16_bf16 v[34:49], v[110:113], v[114:117], v[34:49]
	v_mov_b64_e32 v[114:115], v[182:183]
	v_mov_b64_e32 v[96:97], v[152:153]
	v_mov_b64_e32 v[84:85], v[144:145]
	v_mov_b64_e32 v[104:105], v[192:193]
	v_mov_b64_e32 v[128:129], v[188:189]
	v_mov_b64_e32 v[116:117], v[184:185]
	v_mfma_f32_32x32x16_bf16 v[2:17], v[110:113], v[122:125], v[2:17]
	v_mov_b64_e32 v[110:111], v[154:155]
	s_waitcnt vmcnt(4)
	v_mov_b64_e32 v[122:123], v[178:179]
	v_mov_b64_e32 v[112:113], v[156:157]
	v_mov_b64_e32 v[124:125], v[180:181]
	v_mfma_f32_32x32x16_bf16 v[34:49], v[86:89], v[106:109], v[34:49]
	s_waitcnt vmcnt(2)
	v_mov_b64_e32 v[106:107], v[174:175]
	v_mov_b64_e32 v[108:109], v[176:177]
	v_mfma_f32_32x32x16_bf16 v[2:17], v[86:89], v[90:93], v[2:17]
	v_mov_b64_e32 v[86:87], v[146:147]
	v_mov_b64_e32 v[90:91], v[162:163]
	v_mov_b64_e32 v[88:89], v[148:149]
	v_mov_b64_e32 v[92:93], v[164:165]
	v_mfma_f32_32x32x16_bf16 v[50:65], v[66:69], v[78:81], v[50:65]
	v_mfma_f32_32x32x16_bf16 v[34:49], v[70:73], v[78:81], v[34:49]
	s_waitcnt vmcnt(1)
	v_mov_b64_e32 v[78:79], v[158:159]
	v_mov_b64_e32 v[80:81], v[160:161]
	v_mfma_f32_32x32x16_bf16 v[18:33], v[66:69], v[74:77], v[18:33]
	v_mov_b64_e32 v[66:67], v[138:139]
	v_mov_b64_e32 v[68:69], v[140:141]
	v_mfma_f32_32x32x16_bf16 v[2:17], v[70:73], v[74:77], v[2:17]
	v_mov_b64_e32 v[70:71], v[130:131]
	s_waitcnt vmcnt(0)
	v_mov_b64_e32 v[74:75], v[134:135]
	v_mov_b64_e32 v[72:73], v[132:133]
	v_mov_b64_e32 v[76:77], v[136:137]
	s_cbranch_vccnz .LBB0_428
	s_mul_hi_i32 s9, s36, 0x38e38e39
	s_lshr_b32 s10, s9, 31
	s_ashr_i32 s9, s9, 3
	s_add_i32 s9, s9, s10
	s_mul_i32 s10, s9, 0xfffff700
	v_lshl_add_u32 v68, s9, 6, v199
	s_add_i32 s10, s10, s4
	v_ashrrev_i32_e32 v69, 31, v68
	v_add_u32_e32 v66, s10, v213
	v_lshlrev_b64 v[68:69], 11, v[68:69]
	v_ashrrev_i32_e32 v67, 31, v66
	v_lshl_add_u64 v[68:69], v[194:195], 0, v[68:69]
	v_lshlrev_b64 v[66:67], 11, v[66:67]
	v_add_co_u32_e32 v70, vcc, s2, v68
	v_lshl_add_u64 v[66:67], v[196:197], 0, v[66:67]
	s_nop 0
	v_addc_co_u32_e32 v71, vcc, 0, v69, vcc
	v_add_co_u32_e32 v72, vcc, s2, v66
	s_nop 1
	v_addc_co_u32_e32 v73, vcc, 0, v67, vcc
	global_load_dwordx4 v[102:105], v[68:69], off
	global_load_dwordx4 v[114:117], v[68:69], off offset:32
	global_load_dwordx4 v[98:101], v[66:67], off
	global_load_dwordx4 v[94:97], v[66:67], off offset:32
	global_load_dwordx4 v[126:129], v[70:71], off
	global_load_dwordx4 v[122:125], v[70:71], off offset:32
	global_load_dwordx4 v[118:121], v[72:73], off
	global_load_dwordx4 v[110:113], v[72:73], off offset:32
	global_load_dwordx4 v[106:109], v[68:69], off offset:64
	global_load_dwordx4 v[78:81], v[68:69], off offset:96
	global_load_dwordx4 v[82:85], v[66:67], off offset:64
	s_nop 0
	global_load_dwordx4 v[66:69], v[66:67], off offset:96
	s_nop 0
	global_load_dwordx4 v[90:93], v[70:71], off offset:64
	global_load_dwordx4 v[74:77], v[70:71], off offset:96
	global_load_dwordx4 v[86:89], v[72:73], off offset:64
	s_nop 0
	global_load_dwordx4 v[70:73], v[72:73], off offset:96
	s_branch .LBB0_428
